# row-wise prefetch extended to the first (x to h) and the final LayerNorm pass
# baseline (speedup 1.0000x reference)
.LBB0_217:
	s_or_b64 exec, exec, s[4:5]
	s_mov_b64 s[4:5], 0
	s_waitcnt lgkmcnt(0)
	v_mov_b32_e32 v0, v162
	s_barrier
	s_lshl_b32 s0, s2, 3
	v_ashrrev_i32_e32 v1, 6, v0
	v_add_u32_e32 v32, s0, v1
	s_movk_i32 s8, 0x4000
	s_mov_b64 s[6:7], 0
	v_cmp_gt_i32_e32 vcc, s8, v32
	v_writelane_b32 v246, s0, 39
	s_and_saveexec_b64 s[8:9], vcc
	s_cbranch_execz .LBB0_222
	s_add_u32 s4, s50, s4
	v_and_b32_e32 v33, 63, v0
	s_addc_u32 s5, s51, s5
	v_lshlrev_b32_e32 v56, 4, v33
	v_mov_b32_e32 v57, 0
	v_lshl_add_u64 v[0:1], s[4:5], 0, v[56:57]
	s_mov_b64 s[10:11], 0x2000
	v_lshl_add_u64 v[34:35], v[0:1], 0, s[10:11]
	s_mov_b64 s[10:11], 0x1000
	v_lshl_add_u64 v[36:37], v[0:1], 0, s[10:11]
	s_movk_i32 s10, 0x2000
	v_add_co_u32_e32 v2, vcc, s10, v0
	global_load_dwordx4 v[20:23], v[34:35], off offset:1024
	s_nop 0
	v_addc_co_u32_e32 v3, vcc, 0, v1, vcc
	global_load_dwordx4 v[16:19], v[2:3], off
	s_movk_i32 s10, 0x1000
	v_add_co_u32_e32 v38, vcc, s10, v0
	s_mov_b64 s[14:15], 0x4100000
	s_nop 0
	v_addc_co_u32_e32 v39, vcc, 0, v1, vcc
	global_load_dwordx4 v[24:27], v[34:35], off offset:2048
	global_load_dwordx4 v[0:3], v[36:37], off offset:1024
	global_load_dwordx4 v[28:31], v[34:35], off offset:3072
	global_load_dwordx4 v[4:7], v[38:39], off
	global_load_dwordx4 v[8:11], v[36:37], off offset:2048
	global_load_dwordx4 v[12:15], v[36:37], off offset:3072
	v_lshl_add_u64 v[36:37], s[52:53], 0, v[56:57]
	v_lshlrev_b32_e32 v56, 3, v33
	s_add_u32 s10, s4, 0x80000
	v_lshl_add_u64 v[38:39], s[4:5], 0, v[56:57]
	s_movk_i32 s12, 0x3fff
	v_mov_b32_e32 v35, 1.0
	v_cmp_eq_u32_e32 vcc, 0, v33
	s_addc_u32 s11, s5, 0
	s_lshl_b32 s13, s30, 3
	v_lshl_add_u64 v[38:39], v[38:39], 0, s[14:15]
	v_mov_b32_e32 v34, v57
	s_waitcnt vmcnt(7)
	v_pk_add_f32 v[44:45], v[20:21], 1.0 op_sel_hi:[1,0]
	v_pk_add_f32 v[46:47], v[22:23], 1.0 op_sel_hi:[1,0]
	s_waitcnt vmcnt(6)
	v_pk_add_f32 v[40:41], v[16:17], 1.0 op_sel_hi:[1,0]
	v_pk_add_f32 v[42:43], v[18:19], 1.0 op_sel_hi:[1,0]
	s_waitcnt vmcnt(5)
	v_pk_add_f32 v[48:49], v[24:25], 1.0 op_sel_hi:[1,0]
	v_pk_add_f32 v[50:51], v[26:27], 1.0 op_sel_hi:[1,0]
	s_waitcnt vmcnt(3)
	v_pk_add_f32 v[52:53], v[28:29], 1.0 op_sel_hi:[1,0]
	v_pk_add_f32 v[54:55], v[30:31], 1.0 op_sel_hi:[1,0]
	v_mov_b32_e32 v114, v32
	v_ashrrev_i32_e32 v115, 31, v32
	v_lshlrev_b64 v[112:113], 12, v[114:115]
	v_lshl_add_u64 v[112:113], v[36:37], 0, v[112:113]
	global_load_dwordx4 v[96:99], v[112:113], off
	global_load_dwordx4 v[100:103], v[112:113], off offset:1024
	global_load_dwordx4 v[104:107], v[112:113], off offset:2048
	global_load_dwordx4 v[108:111], v[112:113], off offset:3072
	s_waitcnt vmcnt(0)
	s_branch .LBB0_220
.LBB0_219:
	s_or_b64 exec, exec, s[4:5]
	v_lshlrev_b64 v[56:57], 11, v[32:33]
	v_add_u32_e32 v32, s13, v32
	v_pk_fma_f32 v[28:29], v[28:29], v[40:41], v[4:5]
	v_pk_fma_f32 v[30:31], v[30:31], v[42:43], v[6:7]
	v_pk_fma_f32 v[24:25], v[24:25], v[44:45], v[0:1]
	v_pk_fma_f32 v[26:27], v[26:27], v[46:47], v[2:3]
	v_pk_fma_f32 v[20:21], v[20:21], v[48:49], v[8:9]
	v_pk_fma_f32 v[22:23], v[22:23], v[50:51], v[10:11]
	v_pk_fma_f32 v[16:17], v[16:17], v[52:53], v[12:13]
	v_pk_fma_f32 v[18:19], v[18:19], v[54:55], v[14:15]
	v_cmp_lt_i32_e64 s[4:5], s12, v32
	v_lshl_add_u64 v[56:57], v[38:39], 0, v[56:57]
	v_cvt_pk_bf16_f32 v28, v28, v29
	v_cvt_pk_bf16_f32 v29, v30, v31
	v_cvt_pk_bf16_f32 v24, v24, v25
	v_cvt_pk_bf16_f32 v25, v26, v27
	v_cvt_pk_bf16_f32 v20, v20, v21
	v_cvt_pk_bf16_f32 v21, v22, v23
	v_cvt_pk_bf16_f32 v16, v16, v17
	v_cvt_pk_bf16_f32 v17, v18, v19
	s_or_b64 s[6:7], s[4:5], s[6:7]
	global_store_dwordx2 v[56:57], v[28:29], off
	global_store_dwordx2 v[56:57], v[24:25], off offset:512
	global_store_dwordx2 v[56:57], v[20:21], off offset:1024
	global_store_dwordx2 v[56:57], v[16:17], off offset:1536
	s_andn2_b64 exec, exec, s[6:7]
	s_cbranch_execz .LBB0_222
	s_waitcnt vmcnt(5)
.LBB0_220:
	v_ashrrev_i32_e32 v33, 31, v32
	v_mov_b64_e32 v[28:29], v[96:97]
	v_mov_b64_e32 v[30:31], v[98:99]
	v_mov_b64_e32 v[24:25], v[100:101]
	v_mov_b64_e32 v[26:27], v[102:103]
	v_mov_b64_e32 v[20:21], v[104:105]
	v_mov_b64_e32 v[22:23], v[106:107]
	v_mov_b64_e32 v[16:17], v[108:109]
	v_mov_b64_e32 v[18:19], v[110:111]
	v_add_u32_e32 v114, s13, v32
	v_min_i32_e32 v114, s12, v114
	v_mov_b32_e32 v115, 0
	v_lshlrev_b64 v[112:113], 12, v[114:115]
	v_lshl_add_u64 v[112:113], v[36:37], 0, v[112:113]
	global_load_dwordx4 v[96:99], v[112:113], off
	global_load_dwordx4 v[100:103], v[112:113], off offset:1024
	global_load_dwordx4 v[104:107], v[112:113], off offset:2048
	global_load_dwordx4 v[108:111], v[112:113], off offset:3072
	s_and_saveexec_b64 s[4:5], vcc
	s_cbranch_execz .LBB0_219
	v_lshl_add_u64 v[56:57], v[32:33], 3, s[10:11]
	global_store_dwordx2 v[56:57], v[34:35], off
	s_branch .LBB0_219

.LBB0_1097:
	v_mov_b32_e32 v0, v162
	v_readlane_b32 s4, v246, 39
	v_ashrrev_i32_e32 v2, 6, v0
	s_nop 0
	v_add_u32_e32 v34, s4, v2
	s_movk_i32 s4, 0x4000
	v_cmp_gt_i32_e32 vcc, s4, v34
	s_and_saveexec_b64 s[4:5], vcc
	s_cbranch_execz .LBB0_1102
	v_readlane_b32 s12, v246, 21
	v_readlane_b32 s13, v246, 22
	s_mov_b64 s[8:9], s[12:13]
	s_add_u32 s8, s8, s6
	s_addc_u32 s9, s9, s7
	v_lshlrev_b32_e32 v35, 2, v0
	s_add_u32 s6, s66, s6
	v_and_b32_e32 v0, 0xfc, v35
	s_addc_u32 s7, s67, s7
	v_lshlrev_b32_e32 v0, 2, v0
	global_load_dwordx4 v[2:5], v0, s[6:7]
	global_load_dwordx4 v[6:9], v0, s[6:7] offset:1024
	global_load_dwordx4 v[10:13], v0, s[8:9]
	global_load_dwordx4 v[14:17], v0, s[8:9] offset:1024
	global_load_dwordx4 v[18:21], v0, s[6:7] offset:2048
	global_load_dwordx4 v[22:25], v0, s[6:7] offset:3072
	global_load_dwordx4 v[26:29], v0, s[8:9] offset:2048
	global_load_dwordx4 v[30:33], v0, s[8:9] offset:3072
	v_readlane_b32 s14, v246, 23
	v_readlane_b32 s15, v246, 24
	v_readlane_b32 s16, v246, 25
	v_readlane_b32 s17, v246, 26
	v_readlane_b32 s18, v246, 27
	v_readlane_b32 s19, v246, 28
	v_readlane_b32 s20, v246, 29
	v_readlane_b32 s21, v246, 30
	v_readlane_b32 s22, v246, 31
	v_readlane_b32 s23, v246, 32
	v_readlane_b32 s24, v246, 33
	v_readlane_b32 s25, v246, 34
	v_readlane_b32 s26, v246, 35
	v_readlane_b32 s27, v246, 36
	v_readlane_b32 s12, v246, 0
	v_lshl_add_u64 v[36:37], s[58:59], 0, v[0:1]
	s_mov_b64 s[6:7], 0x100000
	v_readlane_b32 s26, v246, 14
	v_readlane_b32 s27, v246, 15
	v_lshl_add_u64 v[36:37], v[36:37], 0, s[6:7]
	v_bitop3_b32 v58, v35, 64, v185 bitop3:0x6c
	v_lshl_add_u64 v[38:39], s[26:27], 0, v[0:1]
	v_bitop3_b32 v0, v35, s37, v185 bitop3:0x6c
	v_bitop3_b32 v59, v35, 32, v185 bitop3:0x6c
	v_bitop3_b32 v60, v35, 16, v185 bitop3:0x6c
	v_bitop3_b32 v61, v35, 8, v185 bitop3:0x6c
	s_waitcnt vmcnt(17)
	v_bitop3_b32 v62, v35, 4, v185 bitop3:0x6c
	s_mov_b64 s[6:7], 0
	v_readlane_b32 s13, v246, 1
	v_readlane_b32 s14, v246, 2
	v_readlane_b32 s15, v246, 3
	v_readlane_b32 s16, v246, 4
	v_readlane_b32 s17, v246, 5
	v_readlane_b32 s18, v246, 6
	v_readlane_b32 s19, v246, 7
	v_readlane_b32 s20, v246, 8
	v_readlane_b32 s21, v246, 9
	v_readlane_b32 s22, v246, 10
	v_readlane_b32 s23, v246, 11
	v_readlane_b32 s24, v246, 12
	v_readlane_b32 s25, v246, 13
	v_mov_b32_e32 v114, v34
	v_ashrrev_i32_e32 v115, 31, v34
	v_lshlrev_b64 v[112:113], 12, v[114:115]
	v_lshl_add_u64 v[112:113], v[36:37], 0, v[112:113]
	global_load_dwordx4 v[96:99], v[112:113], off
	global_load_dwordx4 v[100:103], v[112:113], off offset:1024
	global_load_dwordx4 v[104:107], v[112:113], off offset:2048
	global_load_dwordx4 v[108:111], v[112:113], off offset:3072
	s_waitcnt vmcnt(0)
	s_branch .LBB0_1100
.Lrw4_nost:
	s_waitcnt vmcnt(0)
.LBB0_1099:
	v_add_u32_e32 v34, s71, v34
	v_cmp_lt_i32_e32 vcc, s43, v34
	s_or_b64 s[6:7], vcc, s[6:7]
	s_andn2_b64 exec, exec, s[6:7]
	s_cbranch_execz .LBB0_1102
.LBB0_1100:
	v_ashrrev_i32_e32 v35, 31, v34
	v_lshlrev_b64 v[40:41], 12, v[34:35]
	v_mov_b64_e32 v[44:45], v[96:97]
	v_mov_b64_e32 v[46:47], v[98:99]
	v_mov_b64_e32 v[48:49], v[100:101]
	v_mov_b64_e32 v[50:51], v[102:103]
	v_mov_b64_e32 v[52:53], v[104:105]
	v_mov_b64_e32 v[54:55], v[106:107]
	v_mov_b64_e32 v[64:65], v[108:109]
	v_mov_b64_e32 v[66:67], v[110:111]
	v_add_u32_e32 v114, s71, v34
	v_min_i32_e32 v114, s43, v114
	v_mov_b32_e32 v115, 0
	v_lshlrev_b64 v[112:113], 12, v[114:115]
	v_lshl_add_u64 v[112:113], v[36:37], 0, v[112:113]
	global_load_dwordx4 v[96:99], v[112:113], off
	global_load_dwordx4 v[100:103], v[112:113], off offset:1024
	global_load_dwordx4 v[104:107], v[112:113], off offset:2048
	global_load_dwordx4 v[108:111], v[112:113], off offset:3072
	v_readlane_b32 s8, v246, 19
	v_readlane_b32 s9, v246, 20
	s_andn2_b64 vcc, exec, s[8:9]
	v_mov_b32_e32 v70, v44
	v_mov_b32_e32 v71, v48
	v_mov_b32_e32 v72, v45
	v_mov_b32_e32 v73, v49
	v_pk_add_f32 v[70:71], v[70:71], v[72:73]
	v_mov_b32_e32 v72, v46
	v_mov_b32_e32 v73, v50
	v_pk_add_f32 v[70:71], v[70:71], v[72:73]
	v_mov_b32_e32 v72, v47
	v_mov_b32_e32 v73, v51
	v_pk_add_f32 v[70:71], v[70:71], v[72:73]
	s_nop 0
	v_add_f32_e32 v35, 0, v70
	v_add_f32_e32 v35, v35, v71
	v_mov_b32_e32 v42, v52
	v_mov_b32_e32 v43, v64
	v_mov_b32_e32 v56, v53
	v_mov_b32_e32 v57, v65
	v_pk_add_f32 v[42:43], v[42:43], v[56:57]
	v_mov_b32_e32 v56, v54
	v_mov_b32_e32 v57, v66
	v_pk_add_f32 v[42:43], v[42:43], v[56:57]
	v_mov_b32_e32 v56, v55
	v_mov_b32_e32 v57, v67
	v_pk_add_f32 v[42:43], v[42:43], v[56:57]
	s_nop 0
	v_add_f32_e32 v35, v35, v42
	v_add_f32_e32 v35, v35, v43
	ds_bpermute_b32 v42, v0, v35
	s_waitcnt lgkmcnt(0)
	v_add_f32_e32 v35, v35, v42
	ds_bpermute_b32 v42, v58, v35
	s_waitcnt lgkmcnt(0)
	v_add_f32_e32 v35, v35, v42
	ds_bpermute_b32 v42, v59, v35
	s_waitcnt lgkmcnt(0)
	v_add_f32_e32 v35, v35, v42
	ds_bpermute_b32 v42, v60, v35
	s_waitcnt lgkmcnt(0)
	v_add_f32_e32 v35, v35, v42
	ds_bpermute_b32 v42, v61, v35
	s_waitcnt lgkmcnt(0)
	v_add_f32_e32 v35, v35, v42
	ds_bpermute_b32 v42, v62, v35
	s_waitcnt lgkmcnt(0)
	v_add_f32_e32 v35, v35, v42
	v_mul_f32_e32 v68, 0x3a800000, v35
	v_pk_add_f32 v[44:45], v[44:45], v[68:69] op_sel_hi:[1,0] neg_lo:[0,1] neg_hi:[0,1]
	v_pk_add_f32 v[48:49], v[48:49], v[68:69] op_sel_hi:[1,0] neg_lo:[0,1] neg_hi:[0,1]
	v_pk_add_f32 v[42:43], v[46:47], v[68:69] op_sel_hi:[1,0] neg_lo:[0,1] neg_hi:[0,1]
	v_pk_mul_f32 v[70:71], v[44:45], v[44:45]
	v_pk_add_f32 v[46:47], v[50:51], v[68:69] op_sel_hi:[1,0] neg_lo:[0,1] neg_hi:[0,1]
	v_pk_mul_f32 v[74:75], v[48:49], v[48:49]
	v_pk_mul_f32 v[72:73], v[42:43], v[42:43]
	v_pk_mul_f32 v[76:77], v[46:47], v[46:47]
	v_add_f32_e32 v35, v74, v75
	v_add_f32_e32 v63, v70, v71
	v_pk_add_f32 v[52:53], v[52:53], v[68:69] op_sel_hi:[1,0] neg_lo:[0,1] neg_hi:[0,1]
	v_add_f32_e32 v35, v76, v35
	v_add_f32_e32 v63, v72, v63
	v_pk_add_f32 v[50:51], v[54:55], v[68:69] op_sel_hi:[1,0] neg_lo:[0,1] neg_hi:[0,1]
	v_pk_mul_f32 v[78:79], v[52:53], v[52:53]
	v_add_f32_e32 v35, v77, v35
	v_add_f32_e32 v63, v73, v63
	v_pk_mul_f32 v[80:81], v[50:51], v[50:51]
	v_add_f32_e32 v35, v63, v35
	v_add_f32_e32 v63, v78, v79
	v_pk_add_f32 v[56:57], v[64:65], v[68:69] op_sel_hi:[1,0] neg_lo:[0,1] neg_hi:[0,1]
	v_add_f32_e32 v63, v80, v63
	v_pk_add_f32 v[54:55], v[66:67], v[68:69] op_sel_hi:[1,0] neg_lo:[0,1] neg_hi:[0,1]
	v_pk_mul_f32 v[64:65], v[56:57], v[56:57]
	v_add_f32_e32 v63, v81, v63
	v_pk_mul_f32 v[66:67], v[54:55], v[54:55]
	v_add_f32_e32 v35, v63, v35
	v_add_f32_e32 v63, v64, v65
	v_add_f32_e32 v63, v66, v63
	v_add_f32_e32 v63, v67, v63
	v_add_f32_e32 v35, v63, v35
	ds_bpermute_b32 v63, v0, v35
	s_waitcnt lgkmcnt(0)
	v_add_f32_e32 v35, v35, v63
	ds_bpermute_b32 v63, v58, v35
	s_waitcnt lgkmcnt(0)
	v_add_f32_e32 v35, v35, v63
	ds_bpermute_b32 v63, v59, v35
	s_waitcnt lgkmcnt(0)
	v_add_f32_e32 v35, v35, v63
	ds_bpermute_b32 v63, v60, v35
	s_waitcnt lgkmcnt(0)
	v_add_f32_e32 v35, v35, v63
	ds_bpermute_b32 v63, v61, v35
	s_waitcnt lgkmcnt(0)
	v_add_f32_e32 v35, v35, v63
	ds_bpermute_b32 v63, v62, v35
	s_cbranch_vccnz .Lrw4_nost
	s_waitcnt lgkmcnt(0)
	v_add_f32_e32 v35, v35, v63
	v_fmamk_f32 v35, v35, 0x3a800000, v178
	v_mul_f32_e32 v63, 0x4b800000, v35
	v_cmp_gt_f32_e32 vcc, s42, v35
	v_lshl_add_u64 v[64:65], v[38:39], 0, v[40:41]
	s_nop 0
	v_cndmask_b32_e32 v35, v35, v63, vcc
	v_rsq_f32_e32 v35, v35
	s_nop 0
	v_mul_f32_e32 v40, 0x45800000, v35
	v_cndmask_b32_e32 v66, v35, v40, vcc
	v_pk_mul_f32 v[40:41], v[44:45], v[66:67] op_sel_hi:[1,0]
	v_pk_mul_f32 v[42:43], v[42:43], v[66:67] op_sel_hi:[1,0]
	v_pk_fma_f32 v[40:41], v[2:3], v[40:41], v[10:11]
	v_pk_fma_f32 v[42:43], v[4:5], v[42:43], v[12:13]
	global_store_dwordx4 v[64:65], v[40:43], off
	s_nop 1
	v_pk_mul_f32 v[40:41], v[48:49], v[66:67] op_sel_hi:[1,0]
	v_pk_mul_f32 v[42:43], v[46:47], v[66:67] op_sel_hi:[1,0]
	v_pk_fma_f32 v[40:41], v[6:7], v[40:41], v[14:15]
	v_pk_fma_f32 v[42:43], v[8:9], v[42:43], v[16:17]
	global_store_dwordx4 v[64:65], v[40:43], off offset:1024
	s_nop 1
	v_pk_mul_f32 v[40:41], v[52:53], v[66:67] op_sel_hi:[1,0]
	v_pk_mul_f32 v[42:43], v[50:51], v[66:67] op_sel_hi:[1,0]
	v_pk_fma_f32 v[40:41], v[18:19], v[40:41], v[26:27]
	v_pk_fma_f32 v[42:43], v[20:21], v[42:43], v[28:29]
	global_store_dwordx4 v[64:65], v[40:43], off offset:2048
	s_nop 1
	v_pk_mul_f32 v[40:41], v[56:57], v[66:67] op_sel_hi:[1,0]
	v_pk_mul_f32 v[42:43], v[54:55], v[66:67] op_sel_hi:[1,0]
	v_pk_fma_f32 v[40:41], v[22:23], v[40:41], v[30:31]
	v_pk_fma_f32 v[42:43], v[24:25], v[42:43], v[32:33]
	global_store_dwordx4 v[64:65], v[40:43], off offset:3072
	s_waitcnt vmcnt(4)
	s_branch .LBB0_1099
.LBB0_1102:
	s_waitcnt vmcnt(0)
	s_or_b64 exec, exec, s[4:5]
	s_andn2_b64 vcc, exec, s[10:11]
	s_cbranch_vccnz .LBB0_277
